# P5 epilogue stores agent-scope write-through (sc1) so the barrier's L2 writeback has less dirty data
# baseline (speedup 1.0000x reference)
; DEVI unsigned pk2(float lo, float hi) { unsigned r; asm("v_cvt_pk_bf16_f32 %0, %1, %2" : "=v"(r) : "v"(lo), "v"(hi)); return r; }
;   DEVI void operator()(const f32x4 (&acc)[2][2][4][2], const pg8::Unit& u, int wr, int wc, int fr, int fq) const {
;     ...
;     for (int ai = 0; ai < 2; ++ai)
; #pragma unroll
;       for (int m = 0; m < 4; ++m) {
;         const int row = u.pm * 256 + ai * 128 + wr * 64 + m * 16 + fr;
;         const float4* sp = (const float4*)(ssrow + (size_t)row * 16);
;         const float4 a = sp[0], b = sp[1], c = sp[2], d = sp[3];
;         const float ssum = (((a.x + a.y) + (a.z + a.w)) + ((b.x + b.y) + (b.z + b.w))) + (((c.x + c.y) + (c.z + c.w)) + ((d.x + d.y) + (d.z + d.w)));
;         const float rs = rsqrtf(ssum * (1.f / 1024.f) + 1e-6f);
; #pragma unroll
;         for (int bj = 0; bj < 2; ++bj) {
;           const int col = u.pn * 256 + bj * 128 + wc * 32 + fq * 8;
;           float h[8];
; #pragma unroll
;           for (int j = 0; j < 4; ++j) { const float h0 = fmaxf(acc[ai][bj][m][0][j] * rs, 0.f), h1 = fmaxf(acc[ai][bj][m][1][j] * rs, 0.f); h[j] = h0 * h0; h[4 + j] = h1 * h1; }
;           u32x4 w; w.x = pk2(h[0], h[1]); w.y = pk2(h[2], h[3]); w.z = pk2(h[4], h[5]); w.w = pk2(h[6], h[7]);
;           *(u32x4*)(uo + (size_t)row * DFF + col) = w;
;         }
;       }
.LBB0_1974:
	v_lshl_add_u32 v146, s3, 8, v131
	v_ashrrev_i32_e32 v147, 31, v146
	v_lshlrev_b64 v[132:133], 6, v[146:147]
	v_lshl_add_u64 v[162:163], s[54:55], 0, v[132:133]
	global_load_dwordx4 v[132:135], v[162:163], off offset:48
	global_load_dwordx4 v[154:157], v[162:163], off offset:16
	global_load_dwordx4 v[158:161], v[162:163], off offset:32
	s_nop 0
	global_load_dwordx4 v[162:165], v[162:163], off
	v_lshl_or_b32 v148, s2, 8, v151
	v_readlane_b32 s24, v252, 40
	v_readlane_b32 s26, v252, 42
	v_readlane_b32 s27, v252, 43
	v_ashrrev_i32_e32 v149, 31, v148
	s_mov_b64 s[22:23], -1
	v_readlane_b32 s25, v252, 41
	s_waitcnt vmcnt(0)
	v_mov_b32_e32 v167, v158
	v_mov_b32_e32 v166, v162
	v_mov_b32_e32 v158, v163
	v_mov_b32_e32 v162, v164
	v_mov_b32_e32 v163, v160
	v_mov_b32_e32 v160, v165
	v_pk_add_f32 v[158:159], v[166:167], v[158:159]
	v_pk_add_f32 v[160:161], v[162:163], v[160:161]
	s_nop 0
	v_pk_add_f32 v[158:159], v[158:159], v[160:161]
	v_mov_b32_e32 v160, v154
	v_mov_b32_e32 v161, v132
	v_mov_b32_e32 v132, v155
	v_mov_b32_e32 v154, v156
	v_mov_b32_e32 v155, v134
	v_mov_b32_e32 v134, v157
	v_pk_add_f32 v[132:133], v[160:161], v[132:133]
	v_pk_add_f32 v[134:135], v[154:155], v[134:135]
	s_nop 0
	v_pk_add_f32 v[132:133], v[132:133], v[134:135]
	s_nop 0
	v_pk_add_f32 v[132:133], v[158:159], v[132:133]
	s_nop 0
	v_add_f32_e32 v132, v132, v133
	v_fmamk_f32 v132, v132, 0x3a800000, v224
	v_cmp_gt_f32_e32 vcc, s77, v132
	v_mul_f32_e32 v133, 0x4b800000, v132
	s_nop 0
	v_cndmask_b32_e32 v132, v132, v133, vcc
	v_rsq_f32_e32 v132, v132
	s_nop 0
	v_mul_f32_e32 v133, 0x45800000, v132
	v_cndmask_b32_e32 v134, v132, v133, vcc
	v_mul_f32_e32 v122, v122, v134
	v_mul_f32_e32 v123, v123, v134
	v_mul_f32_e32 v124, v124, v134
	v_max_f32_e32 v122, 0, v122
	v_max_f32_e32 v123, 0, v123
	v_max_f32_e32 v124, 0, v124
	v_mul_f32_e32 v126, v126, v134
	v_mul_f32_e32 v135, v122, v122
	v_mul_f32_e32 v122, v127, v134
	v_mul_f32_e32 v127, v123, v123
	v_mul_f32_e32 v123, v128, v134
	v_mul_f32_e32 v128, v124, v124
	v_mul_f32_e32 v124, v129, v134
	v_mul_f32_e32 v125, v125, v134
	v_max_f32_e32 v126, 0, v126
	v_max_f32_e32 v122, 0, v122
	v_max_f32_e32 v123, 0, v123
	v_max_f32_e32 v124, 0, v124
	v_max_f32_e32 v125, 0, v125
	v_lshlrev_b64 v[132:133], 13, v[146:147]
	v_mul_f32_e32 v126, v126, v126
	v_mul_f32_e32 v122, v122, v122
	v_mul_f32_e32 v123, v123, v123
	v_mul_f32_e32 v124, v124, v124
	v_mul_f32_e32 v125, v125, v125
	v_cvt_pk_bf16_f32 v122, v126, v122
	v_cvt_pk_bf16_f32 v123, v123, v124
	v_cvt_pk_bf16_f32 v124, v135, v127
	v_cvt_pk_bf16_f32 v125, v128, v125
	v_lshl_add_u64 v[128:129], s[26:27], 0, v[132:133]
	v_lshlrev_b64 v[126:127], 1, v[148:149]
	v_mul_f32_e32 v114, v114, v134
	v_mul_f32_e32 v115, v115, v134
	v_mul_f32_e32 v116, v116, v134
	v_lshl_add_u64 v[128:129], v[128:129], 0, v[126:127]
	v_max_f32_e32 v114, 0, v114
	v_max_f32_e32 v115, 0, v115
	v_max_f32_e32 v116, 0, v116
	global_store_dwordx4 v[128:129], v[122:125], off sc1
	v_mul_f32_e32 v117, v117, v134
	v_mul_f32_e32 v118, v118, v134
	v_mul_f32_e32 v122, v114, v114
	v_mul_f32_e32 v114, v119, v134
	v_mul_f32_e32 v119, v115, v115
	v_mul_f32_e32 v115, v120, v134
	v_mul_f32_e32 v120, v116, v116
	v_mul_f32_e32 v116, v121, v134
	v_max_f32_e32 v114, 0, v114
	v_max_f32_e32 v115, 0, v115
	v_max_f32_e32 v116, 0, v116
	v_max_f32_e32 v117, 0, v117
	v_max_f32_e32 v118, 0, v118
	v_mul_f32_e32 v114, v114, v114
	v_mul_f32_e32 v115, v115, v115
	v_mul_f32_e32 v116, v116, v116
	v_mul_f32_e32 v117, v117, v117
	v_mul_f32_e32 v118, v118, v118
	v_cvt_pk_bf16_f32 v114, v118, v114
	v_cvt_pk_bf16_f32 v115, v115, v116
	v_cvt_pk_bf16_f32 v116, v122, v119
	v_cvt_pk_bf16_f32 v117, v120, v117
	global_store_dwordx4 v[128:129], v[114:117], off offset:256 sc1
	v_or_b32_e32 v128, 16, v146
	v_ashrrev_i32_e32 v129, 31, v128
	v_lshlrev_b64 v[114:115], 6, v[128:129]
	v_lshl_add_u64 v[148:149], s[54:55], 0, v[114:115]
	global_load_dwordx4 v[114:117], v[148:149], off offset:48
	global_load_dwordx4 v[118:121], v[148:149], off offset:16
	global_load_dwordx4 v[122:125], v[148:149], off offset:32
	global_load_dwordx4 v[132:135], v[148:149], off
	s_waitcnt vmcnt(1)
	v_mov_b32_e32 v149, v122
	s_waitcnt vmcnt(0)
	v_mov_b32_e32 v148, v132
	v_mov_b32_e32 v122, v133
	v_mov_b32_e32 v132, v134
	v_mov_b32_e32 v133, v124
	v_mov_b32_e32 v124, v135
	v_pk_add_f32 v[122:123], v[148:149], v[122:123]
	v_pk_add_f32 v[124:125], v[132:133], v[124:125]
	s_nop 0
	v_pk_add_f32 v[122:123], v[122:123], v[124:125]
	v_mov_b32_e32 v124, v118
	v_mov_b32_e32 v125, v114
	v_mov_b32_e32 v114, v119
	v_mov_b32_e32 v118, v120
	v_mov_b32_e32 v119, v116
	v_mov_b32_e32 v116, v121
	v_pk_add_f32 v[114:115], v[124:125], v[114:115]
	v_pk_add_f32 v[116:117], v[118:119], v[116:117]
	s_nop 0
	v_pk_add_f32 v[114:115], v[114:115], v[116:117]
	s_nop 0
	v_pk_add_f32 v[114:115], v[122:123], v[114:115]
	s_nop 0
	v_add_f32_e32 v114, v114, v115
	v_fmamk_f32 v114, v114, 0x3a800000, v224
	v_cmp_gt_f32_e32 vcc, s77, v114
	v_mul_f32_e32 v115, 0x4b800000, v114
	s_nop 0
	v_cndmask_b32_e32 v114, v114, v115, vcc
	v_rsq_f32_e32 v114, v114
	s_nop 0
	v_mul_f32_e32 v115, 0x45800000, v114
	v_cndmask_b32_e32 v116, v114, v115, vcc
	v_mul_f32_e32 v106, v106, v116
	v_mul_f32_e32 v107, v107, v116
	v_mul_f32_e32 v108, v108, v116
	v_max_f32_e32 v106, 0, v106
	v_max_f32_e32 v107, 0, v107
	v_max_f32_e32 v108, 0, v108
	v_mul_f32_e32 v110, v110, v116
	v_mul_f32_e32 v117, v106, v106
	v_mul_f32_e32 v106, v111, v116
	v_mul_f32_e32 v111, v107, v107
	v_mul_f32_e32 v107, v112, v116
	v_mul_f32_e32 v112, v108, v108
	v_mul_f32_e32 v108, v113, v116
	v_max_f32_e32 v110, 0, v110
	v_max_f32_e32 v106, 0, v106
	v_max_f32_e32 v107, 0, v107
; DEVI unsigned pk2(float lo, float hi) { unsigned r; asm("v_cvt_pk_bf16_f32 %0, %1, %2" : "=v"(r) : "v"(lo), "v"(hi)); return r; }
;   DEVI void operator()(const f32x4 (&acc)[2][2][4][2], const pg8::Unit& u, int wr, int wc, int fr, int fq) const {
;     ...
;     for (int ai = 0; ai < 2; ++ai)
; #pragma unroll
;       for (int m = 0; m < 4; ++m) {
;         const int row = u.pm * 256 + ai * 128 + wr * 64 + m * 16 + fr;
;         const float4* sp = (const float4*)(ssrow + (size_t)row * 16);
;         const float4 a = sp[0], b = sp[1], c = sp[2], d = sp[3];
;         const float ssum = (((a.x + a.y) + (a.z + a.w)) + ((b.x + b.y) + (b.z + b.w))) + (((c.x + c.y) + (c.z + c.w)) + ((d.x + d.y) + (d.z + d.w)));
;         const float rs = rsqrtf(ssum * (1.f / 1024.f) + 1e-6f);
; #pragma unroll
;         for (int bj = 0; bj < 2; ++bj) {
;           const int col = u.pn * 256 + bj * 128 + wc * 32 + fq * 8;
;           float h[8];
; #pragma unroll
;           for (int j = 0; j < 4; ++j) { const float h0 = fmaxf(acc[ai][bj][m][0][j] * rs, 0.f), h1 = fmaxf(acc[ai][bj][m][1][j] * rs, 0.f); h[j] = h0 * h0; h[4 + j] = h1 * h1; }
;           u32x4 w; w.x = pk2(h[0], h[1]); w.y = pk2(h[2], h[3]); w.z = pk2(h[4], h[5]); w.w = pk2(h[6], h[7]);
;           *(u32x4*)(uo + (size_t)row * DFF + col) = w;
;         }
;       }
	v_max_f32_e32 v108, 0, v108
	v_lshlrev_b64 v[114:115], 13, v[128:129]
	v_mul_f32_e32 v110, v110, v110
	v_mul_f32_e32 v106, v106, v106
	v_mul_f32_e32 v107, v107, v107
	v_mul_f32_e32 v109, v109, v116
	v_mul_f32_e32 v108, v108, v108
	v_max_f32_e32 v109, 0, v109
	v_cvt_pk_bf16_f32 v106, v110, v106
	v_cvt_pk_bf16_f32 v107, v107, v108
	v_cvt_pk_bf16_f32 v108, v117, v111
	v_lshl_add_u64 v[110:111], s[26:27], 0, v[114:115]
	v_mul_f32_e32 v98, v98, v116
	v_mul_f32_e32 v99, v99, v116
	v_mul_f32_e32 v100, v100, v116
	v_mul_f32_e32 v109, v109, v109
	v_lshl_add_u64 v[110:111], v[110:111], 0, v[126:127]
	v_max_f32_e32 v98, 0, v98
	v_max_f32_e32 v99, 0, v99
	v_max_f32_e32 v100, 0, v100
	v_cvt_pk_bf16_f32 v109, v112, v109
	global_store_dwordx4 v[110:111], v[106:109], off sc1
	v_mul_f32_e32 v101, v101, v116
	v_mul_f32_e32 v102, v102, v116
	v_mul_f32_e32 v106, v98, v98
	v_mul_f32_e32 v98, v103, v116
	v_mul_f32_e32 v103, v99, v99
	v_mul_f32_e32 v99, v104, v116
	v_mul_f32_e32 v104, v100, v100
	v_mul_f32_e32 v100, v105, v116
	v_max_f32_e32 v98, 0, v98
	v_max_f32_e32 v99, 0, v99
	v_max_f32_e32 v100, 0, v100
	v_max_f32_e32 v101, 0, v101
	v_max_f32_e32 v102, 0, v102
	v_mul_f32_e32 v98, v98, v98
	v_mul_f32_e32 v99, v99, v99
	v_mul_f32_e32 v100, v100, v100
	v_mul_f32_e32 v101, v101, v101
	v_mul_f32_e32 v102, v102, v102
	v_cvt_pk_bf16_f32 v98, v102, v98
	v_cvt_pk_bf16_f32 v99, v99, v100
	v_cvt_pk_bf16_f32 v100, v106, v103
	v_cvt_pk_bf16_f32 v101, v104, v101
	global_store_dwordx4 v[110:111], v[98:101], off offset:256 sc1
	v_or_b32_e32 v110, 32, v146
	v_ashrrev_i32_e32 v111, 31, v110
	v_lshlrev_b64 v[98:99], 6, v[110:111]
	v_lshl_add_u64 v[112:113], s[54:55], 0, v[98:99]
	global_load_dwordx4 v[98:101], v[112:113], off offset:48
	global_load_dwordx4 v[102:105], v[112:113], off offset:16
	global_load_dwordx4 v[106:109], v[112:113], off offset:32
	s_nop 0
	global_load_dwordx4 v[112:115], v[112:113], off
	s_waitcnt vmcnt(1)
	v_mov_b32_e32 v117, v106
	s_waitcnt vmcnt(0)
	v_mov_b32_e32 v116, v112
	v_mov_b32_e32 v106, v113
	v_mov_b32_e32 v112, v114
	v_mov_b32_e32 v113, v108
	v_mov_b32_e32 v108, v115
	v_pk_add_f32 v[106:107], v[116:117], v[106:107]
	v_pk_add_f32 v[108:109], v[112:113], v[108:109]
	s_nop 0
	v_pk_add_f32 v[106:107], v[106:107], v[108:109]
	v_mov_b32_e32 v108, v102
	v_mov_b32_e32 v109, v98
	v_mov_b32_e32 v98, v103
	v_mov_b32_e32 v102, v104
	v_mov_b32_e32 v103, v100
	v_mov_b32_e32 v100, v105
	v_pk_add_f32 v[98:99], v[108:109], v[98:99]
	v_pk_add_f32 v[100:101], v[102:103], v[100:101]
	s_nop 0
	v_pk_add_f32 v[98:99], v[98:99], v[100:101]
	s_nop 0
	v_pk_add_f32 v[98:99], v[106:107], v[98:99]
	s_nop 0
	v_add_f32_e32 v98, v98, v99
	v_fmamk_f32 v98, v98, 0x3a800000, v224
	v_cmp_gt_f32_e32 vcc, s77, v98
	v_mul_f32_e32 v99, 0x4b800000, v98
	s_nop 0
	v_cndmask_b32_e32 v98, v98, v99, vcc
	v_rsq_f32_e32 v98, v98
	s_nop 0
	v_mul_f32_e32 v99, 0x45800000, v98
	v_cndmask_b32_e32 v100, v98, v99, vcc
	v_mul_f32_e32 v90, v90, v100
	v_mul_f32_e32 v91, v91, v100
	v_mul_f32_e32 v92, v92, v100
	v_max_f32_e32 v90, 0, v90
	v_max_f32_e32 v91, 0, v91
	v_max_f32_e32 v92, 0, v92
	v_mul_f32_e32 v94, v94, v100
	v_mul_f32_e32 v101, v90, v90
	v_mul_f32_e32 v90, v95, v100
	v_mul_f32_e32 v95, v91, v91
	v_mul_f32_e32 v91, v96, v100
	v_mul_f32_e32 v96, v92, v92
	v_mul_f32_e32 v92, v97, v100
	v_max_f32_e32 v94, 0, v94
	v_max_f32_e32 v90, 0, v90
	v_max_f32_e32 v91, 0, v91
	v_max_f32_e32 v92, 0, v92
	v_lshlrev_b64 v[98:99], 13, v[110:111]
	v_mul_f32_e32 v94, v94, v94
	v_mul_f32_e32 v90, v90, v90
	v_mul_f32_e32 v91, v91, v91
	v_mul_f32_e32 v93, v93, v100
	v_mul_f32_e32 v92, v92, v92
	v_max_f32_e32 v93, 0, v93
	v_cvt_pk_bf16_f32 v90, v94, v90
	v_cvt_pk_bf16_f32 v91, v91, v92
	v_cvt_pk_bf16_f32 v92, v101, v95
	v_lshl_add_u64 v[94:95], s[26:27], 0, v[98:99]
	v_mul_f32_e32 v82, v82, v100
	v_mul_f32_e32 v83, v83, v100
	v_mul_f32_e32 v84, v84, v100
	v_mul_f32_e32 v93, v93, v93
	v_lshl_add_u64 v[94:95], v[94:95], 0, v[126:127]
	v_max_f32_e32 v82, 0, v82
	v_max_f32_e32 v83, 0, v83
	v_max_f32_e32 v84, 0, v84
	v_cvt_pk_bf16_f32 v93, v96, v93
	global_store_dwordx4 v[94:95], v[90:93], off sc1
	v_mul_f32_e32 v85, v85, v100
	v_mul_f32_e32 v86, v86, v100
	v_mul_f32_e32 v90, v82, v82
	v_mul_f32_e32 v82, v87, v100
	v_mul_f32_e32 v87, v83, v83
	v_mul_f32_e32 v83, v88, v100
	v_mul_f32_e32 v88, v84, v84
	v_mul_f32_e32 v84, v89, v100
	v_max_f32_e32 v82, 0, v82
	v_max_f32_e32 v83, 0, v83
	v_max_f32_e32 v84, 0, v84
	v_max_f32_e32 v85, 0, v85
	v_max_f32_e32 v86, 0, v86
	v_mul_f32_e32 v82, v82, v82
	v_mul_f32_e32 v83, v83, v83
	v_mul_f32_e32 v84, v84, v84
	v_mul_f32_e32 v85, v85, v85
	v_mul_f32_e32 v86, v86, v86
	v_cvt_pk_bf16_f32 v82, v86, v82
	v_cvt_pk_bf16_f32 v83, v83, v84
	v_cvt_pk_bf16_f32 v84, v90, v87
	v_cvt_pk_bf16_f32 v85, v88, v85
	global_store_dwordx4 v[94:95], v[82:85], off offset:256 sc1
	v_or_b32_e32 v94, 48, v146
	v_ashrrev_i32_e32 v95, 31, v94
	v_lshlrev_b64 v[82:83], 6, v[94:95]
	v_lshl_add_u64 v[96:97], s[54:55], 0, v[82:83]
	global_load_dwordx4 v[82:85], v[96:97], off offset:48
	global_load_dwordx4 v[86:89], v[96:97], off offset:16
	global_load_dwordx4 v[90:93], v[96:97], off offset:32
	s_nop 0
	global_load_dwordx4 v[96:99], v[96:97], off
	s_waitcnt vmcnt(1)
	v_mov_b32_e32 v101, v90
	s_waitcnt vmcnt(0)
; DEVI unsigned pk2(float lo, float hi) { unsigned r; asm("v_cvt_pk_bf16_f32 %0, %1, %2" : "=v"(r) : "v"(lo), "v"(hi)); return r; }
;   DEVI void operator()(const f32x4 (&acc)[2][2][4][2], const pg8::Unit& u, int wr, int wc, int fr, int fq) const {
;     ...
;     for (int ai = 0; ai < 2; ++ai)
; #pragma unroll
;       for (int m = 0; m < 4; ++m) {
;         const int row = u.pm * 256 + ai * 128 + wr * 64 + m * 16 + fr;
;         const float4* sp = (const float4*)(ssrow + (size_t)row * 16);
;         const float4 a = sp[0], b = sp[1], c = sp[2], d = sp[3];
;         const float ssum = (((a.x + a.y) + (a.z + a.w)) + ((b.x + b.y) + (b.z + b.w))) + (((c.x + c.y) + (c.z + c.w)) + ((d.x + d.y) + (d.z + d.w)));
;         const float rs = rsqrtf(ssum * (1.f / 1024.f) + 1e-6f);
; #pragma unroll
;         for (int bj = 0; bj < 2; ++bj) {
;           const int col = u.pn * 256 + bj * 128 + wc * 32 + fq * 8;
;           float h[8];
; #pragma unroll
;           for (int j = 0; j < 4; ++j) { const float h0 = fmaxf(acc[ai][bj][m][0][j] * rs, 0.f), h1 = fmaxf(acc[ai][bj][m][1][j] * rs, 0.f); h[j] = h0 * h0; h[4 + j] = h1 * h1; }
;           u32x4 w; w.x = pk2(h[0], h[1]); w.y = pk2(h[2], h[3]); w.z = pk2(h[4], h[5]); w.w = pk2(h[6], h[7]);
;           *(u32x4*)(uo + (size_t)row * DFF + col) = w;
;         }
;       }
	v_mov_b32_e32 v100, v96
	v_mov_b32_e32 v90, v97
	v_mov_b32_e32 v96, v98
	v_mov_b32_e32 v97, v92
	v_mov_b32_e32 v92, v99
	v_pk_add_f32 v[90:91], v[100:101], v[90:91]
	v_pk_add_f32 v[92:93], v[96:97], v[92:93]
	s_nop 0
	v_pk_add_f32 v[90:91], v[90:91], v[92:93]
	v_mov_b32_e32 v92, v86
	v_mov_b32_e32 v93, v82
	v_mov_b32_e32 v82, v87
	v_mov_b32_e32 v86, v88
	v_mov_b32_e32 v87, v84
	v_mov_b32_e32 v84, v89
	v_pk_add_f32 v[82:83], v[92:93], v[82:83]
	v_pk_add_f32 v[84:85], v[86:87], v[84:85]
	s_nop 0
	v_pk_add_f32 v[82:83], v[82:83], v[84:85]
	s_nop 0
	v_pk_add_f32 v[82:83], v[90:91], v[82:83]
	s_nop 0
	v_add_f32_e32 v82, v82, v83
	v_fmamk_f32 v82, v82, 0x3a800000, v224
	v_cmp_gt_f32_e32 vcc, s77, v82
	v_mul_f32_e32 v83, 0x4b800000, v82
	s_nop 0
	v_cndmask_b32_e32 v82, v82, v83, vcc
	v_rsq_f32_e32 v82, v82
	s_nop 0
	v_mul_f32_e32 v83, 0x45800000, v82
	v_cndmask_b32_e32 v84, v82, v83, vcc
	v_mul_f32_e32 v74, v74, v84
	v_mul_f32_e32 v75, v75, v84
	v_mul_f32_e32 v76, v76, v84
	v_max_f32_e32 v74, 0, v74
	v_max_f32_e32 v75, 0, v75
	v_max_f32_e32 v76, 0, v76
	v_mul_f32_e32 v78, v78, v84
	v_mul_f32_e32 v85, v74, v74
	v_mul_f32_e32 v74, v79, v84
	v_mul_f32_e32 v79, v75, v75
	v_mul_f32_e32 v75, v80, v84
	v_mul_f32_e32 v80, v76, v76
	v_mul_f32_e32 v76, v81, v84
	v_max_f32_e32 v78, 0, v78
	v_max_f32_e32 v74, 0, v74
	v_max_f32_e32 v75, 0, v75
	v_max_f32_e32 v76, 0, v76
	v_lshlrev_b64 v[82:83], 13, v[94:95]
	v_mul_f32_e32 v78, v78, v78
	v_mul_f32_e32 v74, v74, v74
	v_mul_f32_e32 v75, v75, v75
	v_mul_f32_e32 v77, v77, v84
	v_mul_f32_e32 v76, v76, v76
	v_max_f32_e32 v77, 0, v77
	v_cvt_pk_bf16_f32 v74, v78, v74
	v_cvt_pk_bf16_f32 v75, v75, v76
	v_cvt_pk_bf16_f32 v76, v85, v79
	v_lshl_add_u64 v[78:79], s[26:27], 0, v[82:83]
	v_mul_f32_e32 v66, v66, v84
	v_mul_f32_e32 v67, v67, v84
	v_mul_f32_e32 v68, v68, v84
	v_mul_f32_e32 v77, v77, v77
	v_lshl_add_u64 v[78:79], v[78:79], 0, v[126:127]
	v_max_f32_e32 v66, 0, v66
	v_max_f32_e32 v67, 0, v67
	v_max_f32_e32 v68, 0, v68
	v_cvt_pk_bf16_f32 v77, v80, v77
	global_store_dwordx4 v[78:79], v[74:77], off sc1
	v_mul_f32_e32 v69, v69, v84
	v_mul_f32_e32 v70, v70, v84
	v_mul_f32_e32 v74, v66, v66
	v_mul_f32_e32 v66, v71, v84
	v_mul_f32_e32 v71, v67, v67
	v_mul_f32_e32 v67, v72, v84
	v_mul_f32_e32 v72, v68, v68
	v_mul_f32_e32 v68, v73, v84
	v_max_f32_e32 v66, 0, v66
	v_max_f32_e32 v67, 0, v67
	v_max_f32_e32 v68, 0, v68
	v_max_f32_e32 v69, 0, v69
	v_max_f32_e32 v70, 0, v70
	v_mul_f32_e32 v66, v66, v66
	v_mul_f32_e32 v67, v67, v67
	v_mul_f32_e32 v68, v68, v68
	v_mul_f32_e32 v69, v69, v69
	v_mul_f32_e32 v70, v70, v70
	v_cvt_pk_bf16_f32 v66, v70, v66
	v_cvt_pk_bf16_f32 v67, v67, v68
	v_cvt_pk_bf16_f32 v68, v74, v71
	v_cvt_pk_bf16_f32 v69, v72, v69
	global_store_dwordx4 v[78:79], v[66:69], off offset:256 sc1
	v_add_u32_e32 v78, 0x80, v146
	v_ashrrev_i32_e32 v79, 31, v78
	v_lshlrev_b64 v[66:67], 6, v[78:79]
	v_lshl_add_u64 v[80:81], s[54:55], 0, v[66:67]
	global_load_dwordx4 v[66:69], v[80:81], off offset:48
	global_load_dwordx4 v[70:73], v[80:81], off offset:16
	global_load_dwordx4 v[74:77], v[80:81], off offset:32
	s_nop 0
	global_load_dwordx4 v[80:83], v[80:81], off
	s_waitcnt vmcnt(1)
	v_mov_b32_e32 v85, v74
	s_waitcnt vmcnt(0)
	v_mov_b32_e32 v84, v80
	v_mov_b32_e32 v74, v81
	v_mov_b32_e32 v80, v82
	v_mov_b32_e32 v81, v76
	v_mov_b32_e32 v76, v83
	v_pk_add_f32 v[74:75], v[84:85], v[74:75]
	v_pk_add_f32 v[76:77], v[80:81], v[76:77]
	s_nop 0
	v_pk_add_f32 v[74:75], v[74:75], v[76:77]
	v_mov_b32_e32 v76, v70
	v_mov_b32_e32 v77, v66
	v_mov_b32_e32 v66, v71
	v_mov_b32_e32 v70, v72
	v_mov_b32_e32 v71, v68
	v_mov_b32_e32 v68, v73
	v_pk_add_f32 v[66:67], v[76:77], v[66:67]
	v_pk_add_f32 v[68:69], v[70:71], v[68:69]
	s_nop 0
	v_pk_add_f32 v[66:67], v[66:67], v[68:69]
	s_nop 0
	v_pk_add_f32 v[66:67], v[74:75], v[66:67]
	s_nop 0
	v_add_f32_e32 v66, v66, v67
	v_fmamk_f32 v66, v66, 0x3a800000, v224
	v_cmp_gt_f32_e32 vcc, s77, v66
	v_mul_f32_e32 v67, 0x4b800000, v66
	s_nop 0
	v_cndmask_b32_e32 v66, v66, v67, vcc
	v_rsq_f32_e32 v66, v66
	s_nop 0
	v_mul_f32_e32 v67, 0x45800000, v66
	v_cndmask_b32_e32 v68, v66, v67, vcc
	v_mul_f32_e32 v58, v58, v68
	v_mul_f32_e32 v59, v59, v68
	v_mul_f32_e32 v60, v60, v68
	v_max_f32_e32 v58, 0, v58
	v_max_f32_e32 v59, 0, v59
	v_max_f32_e32 v60, 0, v60
	v_mul_f32_e32 v62, v62, v68
	v_mul_f32_e32 v69, v58, v58
	v_mul_f32_e32 v58, v63, v68
	v_mul_f32_e32 v63, v59, v59
	v_mul_f32_e32 v59, v64, v68
	v_mul_f32_e32 v64, v60, v60
	v_mul_f32_e32 v60, v65, v68
	v_max_f32_e32 v62, 0, v62
	v_max_f32_e32 v58, 0, v58
	v_max_f32_e32 v59, 0, v59
	v_max_f32_e32 v60, 0, v60
	v_lshlrev_b64 v[66:67], 13, v[78:79]
	v_mul_f32_e32 v62, v62, v62
	v_mul_f32_e32 v58, v58, v58
	v_mul_f32_e32 v59, v59, v59
	v_mul_f32_e32 v61, v61, v68
	v_mul_f32_e32 v60, v60, v60
	v_max_f32_e32 v61, 0, v61
	v_cvt_pk_bf16_f32 v58, v62, v58
	v_cvt_pk_bf16_f32 v59, v59, v60
	v_cvt_pk_bf16_f32 v60, v69, v63
	v_lshl_add_u64 v[62:63], s[26:27], 0, v[66:67]
	v_mul_f32_e32 v50, v50, v68
	v_mul_f32_e32 v51, v51, v68
	v_mul_f32_e32 v52, v52, v68
	v_mul_f32_e32 v61, v61, v61
	v_lshl_add_u64 v[62:63], v[62:63], 0, v[126:127]
	v_max_f32_e32 v50, 0, v50
	v_max_f32_e32 v51, 0, v51
	v_max_f32_e32 v52, 0, v52
	v_cvt_pk_bf16_f32 v61, v64, v61
	global_store_dwordx4 v[62:63], v[58:61], off sc1
	v_mul_f32_e32 v53, v53, v68
	v_mul_f32_e32 v54, v54, v68
	v_mul_f32_e32 v58, v50, v50
	v_mul_f32_e32 v50, v55, v68
	v_mul_f32_e32 v55, v51, v51
	v_mul_f32_e32 v51, v56, v68
	v_mul_f32_e32 v56, v52, v52
	v_mul_f32_e32 v52, v57, v68
	v_max_f32_e32 v50, 0, v50
	v_max_f32_e32 v51, 0, v51
	v_max_f32_e32 v52, 0, v52
	v_max_f32_e32 v53, 0, v53
	v_max_f32_e32 v54, 0, v54
	v_mul_f32_e32 v50, v50, v50
	v_mul_f32_e32 v51, v51, v51
	v_mul_f32_e32 v52, v52, v52
	v_mul_f32_e32 v53, v53, v53
	v_mul_f32_e32 v54, v54, v54
	v_cvt_pk_bf16_f32 v50, v54, v50
	v_cvt_pk_bf16_f32 v51, v51, v52
	v_cvt_pk_bf16_f32 v52, v58, v55
	v_cvt_pk_bf16_f32 v53, v56, v53
	global_store_dwordx4 v[62:63], v[50:53], off offset:256 sc1
	v_add_u32_e32 v62, 0x90, v146
	v_ashrrev_i32_e32 v63, 31, v62
	v_lshlrev_b64 v[50:51], 6, v[62:63]
	v_lshl_add_u64 v[64:65], s[54:55], 0, v[50:51]
	global_load_dwordx4 v[50:53], v[64:65], off offset:48
	global_load_dwordx4 v[54:57], v[64:65], off offset:16
	global_load_dwordx4 v[58:61], v[64:65], off offset:32
	s_nop 0
	global_load_dwordx4 v[64:67], v[64:65], off
	s_waitcnt vmcnt(1)
; DEVI unsigned pk2(float lo, float hi) { unsigned r; asm("v_cvt_pk_bf16_f32 %0, %1, %2" : "=v"(r) : "v"(lo), "v"(hi)); return r; }
;   DEVI void operator()(const f32x4 (&acc)[2][2][4][2], const pg8::Unit& u, int wr, int wc, int fr, int fq) const {
;     ...
;     for (int ai = 0; ai < 2; ++ai)
; #pragma unroll
;       for (int m = 0; m < 4; ++m) {
;         const int row = u.pm * 256 + ai * 128 + wr * 64 + m * 16 + fr;
;         const float4* sp = (const float4*)(ssrow + (size_t)row * 16);
;         const float4 a = sp[0], b = sp[1], c = sp[2], d = sp[3];
;         const float ssum = (((a.x + a.y) + (a.z + a.w)) + ((b.x + b.y) + (b.z + b.w))) + (((c.x + c.y) + (c.z + c.w)) + ((d.x + d.y) + (d.z + d.w)));
;         const float rs = rsqrtf(ssum * (1.f / 1024.f) + 1e-6f);
; #pragma unroll
;         for (int bj = 0; bj < 2; ++bj) {
;           const int col = u.pn * 256 + bj * 128 + wc * 32 + fq * 8;
;           float h[8];
; #pragma unroll
;           for (int j = 0; j < 4; ++j) { const float h0 = fmaxf(acc[ai][bj][m][0][j] * rs, 0.f), h1 = fmaxf(acc[ai][bj][m][1][j] * rs, 0.f); h[j] = h0 * h0; h[4 + j] = h1 * h1; }
;           u32x4 w; w.x = pk2(h[0], h[1]); w.y = pk2(h[2], h[3]); w.z = pk2(h[4], h[5]); w.w = pk2(h[6], h[7]);
;           *(u32x4*)(uo + (size_t)row * DFF + col) = w;
;         }
;       }
	v_mov_b32_e32 v69, v58
	s_waitcnt vmcnt(0)
	v_mov_b32_e32 v68, v64
	v_mov_b32_e32 v58, v65
	v_mov_b32_e32 v64, v66
	v_mov_b32_e32 v65, v60
	v_mov_b32_e32 v60, v67
	v_pk_add_f32 v[58:59], v[68:69], v[58:59]
	v_pk_add_f32 v[60:61], v[64:65], v[60:61]
	s_nop 0
	v_pk_add_f32 v[58:59], v[58:59], v[60:61]
	v_mov_b32_e32 v60, v54
	v_mov_b32_e32 v61, v50
	v_mov_b32_e32 v50, v55
	v_mov_b32_e32 v54, v56
	v_mov_b32_e32 v55, v52
	v_mov_b32_e32 v52, v57
	v_pk_add_f32 v[50:51], v[60:61], v[50:51]
	v_pk_add_f32 v[52:53], v[54:55], v[52:53]
	s_nop 0
	v_pk_add_f32 v[50:51], v[50:51], v[52:53]
	s_nop 0
	v_pk_add_f32 v[50:51], v[58:59], v[50:51]
	s_nop 0
	v_add_f32_e32 v50, v50, v51
	v_fmamk_f32 v50, v50, 0x3a800000, v224
	v_cmp_gt_f32_e32 vcc, s77, v50
	v_mul_f32_e32 v51, 0x4b800000, v50
	s_nop 0
	v_cndmask_b32_e32 v50, v50, v51, vcc
	v_rsq_f32_e32 v50, v50
	s_nop 0
	v_mul_f32_e32 v51, 0x45800000, v50
	v_cndmask_b32_e32 v52, v50, v51, vcc
	v_mul_f32_e32 v42, v42, v52
	v_mul_f32_e32 v43, v43, v52
	v_mul_f32_e32 v44, v44, v52
	v_max_f32_e32 v42, 0, v42
	v_max_f32_e32 v43, 0, v43
	v_max_f32_e32 v44, 0, v44
	v_mul_f32_e32 v46, v46, v52
	v_mul_f32_e32 v53, v42, v42
	v_mul_f32_e32 v42, v47, v52
	v_mul_f32_e32 v47, v43, v43
	v_mul_f32_e32 v43, v48, v52
	v_mul_f32_e32 v48, v44, v44
	v_mul_f32_e32 v44, v49, v52
	v_max_f32_e32 v46, 0, v46
	v_max_f32_e32 v42, 0, v42
	v_max_f32_e32 v43, 0, v43
	v_max_f32_e32 v44, 0, v44
	v_lshlrev_b64 v[50:51], 13, v[62:63]
	v_mul_f32_e32 v46, v46, v46
	v_mul_f32_e32 v42, v42, v42
	v_mul_f32_e32 v43, v43, v43
	v_mul_f32_e32 v45, v45, v52
	v_mul_f32_e32 v44, v44, v44
	v_max_f32_e32 v45, 0, v45
	v_cvt_pk_bf16_f32 v42, v46, v42
	v_cvt_pk_bf16_f32 v43, v43, v44
	v_cvt_pk_bf16_f32 v44, v53, v47
	v_lshl_add_u64 v[46:47], s[26:27], 0, v[50:51]
	v_mul_f32_e32 v34, v34, v52
	v_mul_f32_e32 v35, v35, v52
	v_mul_f32_e32 v36, v36, v52
	v_mul_f32_e32 v45, v45, v45
	v_lshl_add_u64 v[46:47], v[46:47], 0, v[126:127]
	v_max_f32_e32 v34, 0, v34
	v_max_f32_e32 v35, 0, v35
	v_max_f32_e32 v36, 0, v36
	v_cvt_pk_bf16_f32 v45, v48, v45
	global_store_dwordx4 v[46:47], v[42:45], off sc1
	v_mul_f32_e32 v37, v37, v52
	v_mul_f32_e32 v38, v38, v52
	v_mul_f32_e32 v42, v34, v34
	v_mul_f32_e32 v34, v39, v52
	v_mul_f32_e32 v39, v35, v35
	v_mul_f32_e32 v35, v40, v52
	v_mul_f32_e32 v40, v36, v36
	v_mul_f32_e32 v36, v41, v52
	v_max_f32_e32 v34, 0, v34
	v_max_f32_e32 v35, 0, v35
	v_max_f32_e32 v36, 0, v36
	v_max_f32_e32 v37, 0, v37
	v_max_f32_e32 v38, 0, v38
	v_mul_f32_e32 v34, v34, v34
	v_mul_f32_e32 v35, v35, v35
	v_mul_f32_e32 v36, v36, v36
	v_mul_f32_e32 v37, v37, v37
	v_mul_f32_e32 v38, v38, v38
	v_cvt_pk_bf16_f32 v34, v38, v34
	v_cvt_pk_bf16_f32 v35, v35, v36
	v_cvt_pk_bf16_f32 v36, v42, v39
	v_cvt_pk_bf16_f32 v37, v40, v37
	global_store_dwordx4 v[46:47], v[34:37], off offset:256 sc1
	v_add_u32_e32 v46, 0xa0, v146
	v_ashrrev_i32_e32 v47, 31, v46
	v_lshlrev_b64 v[34:35], 6, v[46:47]
	v_lshl_add_u64 v[48:49], s[54:55], 0, v[34:35]
	global_load_dwordx4 v[34:37], v[48:49], off offset:48
	global_load_dwordx4 v[38:41], v[48:49], off offset:16
	global_load_dwordx4 v[42:45], v[48:49], off offset:32
	s_nop 0
	global_load_dwordx4 v[48:51], v[48:49], off
	s_waitcnt vmcnt(1)
	v_mov_b32_e32 v53, v42
	s_waitcnt vmcnt(0)
; DEVI unsigned pk2(float lo, float hi) { unsigned r; asm("v_cvt_pk_bf16_f32 %0, %1, %2" : "=v"(r) : "v"(lo), "v"(hi)); return r; }
; #define PG8_BAR __builtin_amdgcn_s_barrier()
; template <class Epi, class Sched, bool ALIGN_EPI = false, bool SP2 = false>
; __device__ __forceinline__ void gemm_phase(PG8_LAS unsigned char* lds, const Gemm g, const Sched& S, const Epi& E, int tid_in) {
;     ...
;         if constexpr (ALIGN_EPI) { if (wr == 0) PG8_BAR; }
;         if constexpr (!Epi::AFTER_DRAIN) { E(acc, cur, wr, wc, fr, fq); S.done(cur); }
;         if (!has_next) break;
; #pragma unroll
;         for (int a = 0; a < 2; ++a)
; #pragma unroll
;             for (int b = 0; b < 2; ++b)
; #pragma unroll
;                 for (int m = 0; m < 4; ++m)
; #pragma unroll
;                     for (int n = 0; n < 2; ++n) acc[a][b][m][n] = (f32x4){0.f, 0.f, 0.f, 0.f};
;         cur = nxt; cA = nA; cB = nB; ++ui;
;         if constexpr (ALIGN_EPI) { if (wr == 1) PG8_BAR; }
;   DEVI void operator()(const f32x4 (&acc)[2][2][4][2], const pg8::Unit& u, int wr, int wc, int fr, int fq) const {
;     ...
;     for (int ai = 0; ai < 2; ++ai)
; #pragma unroll
;       for (int m = 0; m < 4; ++m) {
;         const int row = u.pm * 256 + ai * 128 + wr * 64 + m * 16 + fr;
;         const float4* sp = (const float4*)(ssrow + (size_t)row * 16);
;         const float4 a = sp[0], b = sp[1], c = sp[2], d = sp[3];
;         const float ssum = (((a.x + a.y) + (a.z + a.w)) + ((b.x + b.y) + (b.z + b.w))) + (((c.x + c.y) + (c.z + c.w)) + ((d.x + d.y) + (d.z + d.w)));
;         const float rs = rsqrtf(ssum * (1.f / 1024.f) + 1e-6f);
; #pragma unroll
;         for (int bj = 0; bj < 2; ++bj) {
;           const int col = u.pn * 256 + bj * 128 + wc * 32 + fq * 8;
;           float h[8];
; #pragma unroll
;           for (int j = 0; j < 4; ++j) { const float h0 = fmaxf(acc[ai][bj][m][0][j] * rs, 0.f), h1 = fmaxf(acc[ai][bj][m][1][j] * rs, 0.f); h[j] = h0 * h0; h[4 + j] = h1 * h1; }
;           u32x4 w; w.x = pk2(h[0], h[1]); w.y = pk2(h[2], h[3]); w.z = pk2(h[4], h[5]); w.w = pk2(h[6], h[7]);
;           *(u32x4*)(uo + (size_t)row * DFF + col) = w;
;         }
;       }
	v_mov_b32_e32 v52, v48
	v_mov_b32_e32 v42, v49
	v_mov_b32_e32 v48, v50
	v_mov_b32_e32 v49, v44
	v_mov_b32_e32 v44, v51
	v_pk_add_f32 v[42:43], v[52:53], v[42:43]
	v_pk_add_f32 v[44:45], v[48:49], v[44:45]
	s_nop 0
	v_pk_add_f32 v[42:43], v[42:43], v[44:45]
	v_mov_b32_e32 v44, v38
	v_mov_b32_e32 v45, v34
	v_mov_b32_e32 v34, v39
	v_mov_b32_e32 v38, v40
	v_mov_b32_e32 v39, v36
	v_mov_b32_e32 v36, v41
	v_pk_add_f32 v[34:35], v[44:45], v[34:35]
	v_pk_add_f32 v[36:37], v[38:39], v[36:37]
	s_nop 0
	v_pk_add_f32 v[34:35], v[34:35], v[36:37]
	s_nop 0
	v_pk_add_f32 v[34:35], v[42:43], v[34:35]
	s_nop 0
	v_add_f32_e32 v34, v34, v35
	v_fmamk_f32 v34, v34, 0x3a800000, v224
	v_cmp_gt_f32_e32 vcc, s77, v34
	v_mul_f32_e32 v35, 0x4b800000, v34
	s_nop 0
	v_cndmask_b32_e32 v34, v34, v35, vcc
	v_rsq_f32_e32 v34, v34
	s_nop 0
	v_mul_f32_e32 v35, 0x45800000, v34
	v_cndmask_b32_e32 v36, v34, v35, vcc
	v_mul_f32_e32 v24, v24, v36
	v_mul_f32_e32 v25, v25, v36
	v_mul_f32_e32 v26, v26, v36
	v_max_f32_e32 v24, 0, v24
	v_max_f32_e32 v25, 0, v25
	v_max_f32_e32 v26, 0, v26
	v_mul_f32_e32 v28, v28, v36
	v_mul_f32_e32 v37, v24, v24
	v_mul_f32_e32 v24, v29, v36
	v_mul_f32_e32 v29, v25, v25
	v_mul_f32_e32 v25, v30, v36
	v_mul_f32_e32 v30, v26, v26
	v_mul_f32_e32 v26, v31, v36
	v_max_f32_e32 v28, 0, v28
	v_max_f32_e32 v24, 0, v24
	v_max_f32_e32 v25, 0, v25
	v_max_f32_e32 v26, 0, v26
	v_lshlrev_b64 v[34:35], 13, v[46:47]
	v_mul_f32_e32 v28, v28, v28
	v_mul_f32_e32 v24, v24, v24
	v_mul_f32_e32 v25, v25, v25
	v_mul_f32_e32 v27, v27, v36
	v_mul_f32_e32 v26, v26, v26
	v_max_f32_e32 v27, 0, v27
	v_cvt_pk_bf16_f32 v24, v28, v24
	v_cvt_pk_bf16_f32 v25, v25, v26
	v_cvt_pk_bf16_f32 v26, v37, v29
	v_lshl_add_u64 v[28:29], s[26:27], 0, v[34:35]
	v_mul_f32_e32 v16, v16, v36
	v_mul_f32_e32 v17, v17, v36
	v_mul_f32_e32 v18, v18, v36
	v_mul_f32_e32 v27, v27, v27
	v_lshl_add_u64 v[28:29], v[28:29], 0, v[126:127]
	v_max_f32_e32 v16, 0, v16
	v_max_f32_e32 v17, 0, v17
	v_max_f32_e32 v18, 0, v18
	v_cvt_pk_bf16_f32 v27, v30, v27
	global_store_dwordx4 v[28:29], v[24:27], off sc1
	v_mul_f32_e32 v19, v19, v36
	v_mul_f32_e32 v20, v20, v36
	v_mul_f32_e32 v24, v16, v16
	v_mul_f32_e32 v16, v21, v36
	v_mul_f32_e32 v21, v17, v17
	v_mul_f32_e32 v17, v22, v36
	v_mul_f32_e32 v22, v18, v18
	v_mul_f32_e32 v18, v23, v36
	v_max_f32_e32 v16, 0, v16
	v_max_f32_e32 v17, 0, v17
	v_max_f32_e32 v18, 0, v18
	v_max_f32_e32 v19, 0, v19
	v_max_f32_e32 v20, 0, v20
	v_mul_f32_e32 v16, v16, v16
	v_mul_f32_e32 v17, v17, v17
	v_mul_f32_e32 v18, v18, v18
	v_mul_f32_e32 v19, v19, v19
	v_mul_f32_e32 v20, v20, v20
	v_cvt_pk_bf16_f32 v16, v20, v16
	v_cvt_pk_bf16_f32 v17, v17, v18
	v_cvt_pk_bf16_f32 v18, v24, v21
	v_cvt_pk_bf16_f32 v19, v22, v19
	global_store_dwordx4 v[28:29], v[16:19], off offset:256 sc1
	v_add_u32_e32 v28, 0xb0, v146
	v_ashrrev_i32_e32 v29, 31, v28
	v_lshlrev_b64 v[16:17], 6, v[28:29]
	v_lshl_add_u64 v[30:31], s[54:55], 0, v[16:17]
	global_load_dwordx4 v[16:19], v[30:31], off offset:48
	global_load_dwordx4 v[20:23], v[30:31], off offset:16
	global_load_dwordx4 v[24:27], v[30:31], off offset:32
	global_load_dwordx4 v[34:37], v[30:31], off
	s_waitcnt vmcnt(1)
	v_mov_b32_e32 v31, v24
	s_waitcnt vmcnt(0)
	v_mov_b32_e32 v30, v34
	v_mov_b32_e32 v24, v35
	v_pk_add_f32 v[24:25], v[30:31], v[24:25]
	v_mov_b32_e32 v30, v36
	v_mov_b32_e32 v31, v26
	v_mov_b32_e32 v26, v37
	v_pk_add_f32 v[26:27], v[30:31], v[26:27]
	s_nop 0
	v_pk_add_f32 v[24:25], v[24:25], v[26:27]
	v_mov_b32_e32 v26, v20
	v_mov_b32_e32 v27, v16
	v_mov_b32_e32 v16, v21
	v_mov_b32_e32 v20, v22
	v_mov_b32_e32 v21, v18
	v_mov_b32_e32 v18, v23
	v_pk_add_f32 v[16:17], v[26:27], v[16:17]
	v_pk_add_f32 v[18:19], v[20:21], v[18:19]
	s_nop 0
	v_pk_add_f32 v[16:17], v[16:17], v[18:19]
	s_nop 0
	v_pk_add_f32 v[16:17], v[24:25], v[16:17]
	s_nop 0
	v_add_f32_e32 v16, v16, v17
	v_fmamk_f32 v16, v16, 0x3a800000, v224
	v_cmp_gt_f32_e32 vcc, s77, v16
	v_mul_f32_e32 v17, 0x4b800000, v16
	s_nop 0
	v_cndmask_b32_e32 v16, v16, v17, vcc
	v_rsq_f32_e32 v16, v16
	s_nop 0
	v_mul_f32_e32 v17, 0x45800000, v16
	v_cndmask_b32_e32 v18, v16, v17, vcc
	v_mul_f32_e32 v8, v8, v18
	v_mul_f32_e32 v9, v9, v18
	v_mul_f32_e32 v10, v10, v18
	v_max_f32_e32 v8, 0, v8
	v_max_f32_e32 v9, 0, v9
	v_max_f32_e32 v10, 0, v10
	v_mul_f32_e32 v12, v12, v18
	v_mul_f32_e32 v19, v8, v8
	v_mul_f32_e32 v8, v13, v18
	v_mul_f32_e32 v13, v9, v9
	v_mul_f32_e32 v9, v14, v18
	v_mul_f32_e32 v14, v10, v10
	v_mul_f32_e32 v10, v15, v18
	v_max_f32_e32 v12, 0, v12
	v_max_f32_e32 v8, 0, v8
	v_max_f32_e32 v9, 0, v9
	v_max_f32_e32 v10, 0, v10
	v_lshlrev_b64 v[16:17], 13, v[28:29]
	v_mul_f32_e32 v12, v12, v12
	v_mul_f32_e32 v8, v8, v8
	v_mul_f32_e32 v9, v9, v9
	v_mul_f32_e32 v11, v11, v18
	v_mul_f32_e32 v10, v10, v10
	v_max_f32_e32 v11, 0, v11
	v_cvt_pk_bf16_f32 v8, v12, v8
	v_cvt_pk_bf16_f32 v9, v9, v10
	v_cvt_pk_bf16_f32 v10, v19, v13
	v_lshl_add_u64 v[12:13], s[26:27], 0, v[16:17]
	v_mul_f32_e32 v0, v0, v18
	v_mul_f32_e32 v1, v1, v18
	v_mul_f32_e32 v2, v2, v18
	v_mul_f32_e32 v11, v11, v11
	v_lshl_add_u64 v[12:13], v[12:13], 0, v[126:127]
	v_max_f32_e32 v0, 0, v0
	v_max_f32_e32 v1, 0, v1
	v_max_f32_e32 v2, 0, v2
	v_cvt_pk_bf16_f32 v11, v14, v11
	global_store_dwordx4 v[12:13], v[8:11], off sc1
	v_mul_f32_e32 v3, v3, v18
	v_mul_f32_e32 v4, v4, v18
	v_mul_f32_e32 v8, v0, v0
	v_mul_f32_e32 v0, v5, v18
	v_mul_f32_e32 v5, v1, v1
	v_mul_f32_e32 v1, v6, v18
	v_mul_f32_e32 v6, v2, v2
	v_mul_f32_e32 v2, v7, v18
	v_max_f32_e32 v0, 0, v0
	v_max_f32_e32 v1, 0, v1
	v_max_f32_e32 v2, 0, v2
	v_max_f32_e32 v3, 0, v3
	v_max_f32_e32 v4, 0, v4
	v_mul_f32_e32 v0, v0, v0
	v_mul_f32_e32 v1, v1, v1
	v_mul_f32_e32 v2, v2, v2
	v_mul_f32_e32 v3, v3, v3
	s_andn2_b64 vcc, exec, s[4:5]
	v_mul_f32_e32 v4, v4, v4
	v_cvt_pk_bf16_f32 v0, v4, v0
	v_cvt_pk_bf16_f32 v1, v1, v2
	v_cvt_pk_bf16_f32 v2, v8, v5
	v_cvt_pk_bf16_f32 v3, v6, v3
	global_store_dwordx4 v[12:13], v[0:3], off offset:256 sc1
	s_cbranch_vccnz .LBB0_1963
	s_andn2_b64 vcc, exec, s[6:7]
	s_cbranch_vccnz .LBB0_1962
	s_barrier
	s_branch .LBB0_1962
